# hand-rewrote prep x->bf16 conversion: all 8-9 rows' loads issued up front with saddr loads, batched 6-step butterfly across rows
# baseline (speedup 1.0000x reference)
.LBB0_1482:
	v_readlane_b32 s4, v252, 20
	v_readlane_b32 s5, v252, 21
	v_readlane_b32 s12, v253, 3
	v_readlane_b32 s13, v253, 4
	v_readlane_b32 s14, v252, 33
	v_readlane_b32 s15, v252, 34
	v_readlane_b32 s16, v253, 15
	s_load_dwordx4 s[8:11], s[4:5], 0x0
	v_mbcnt_lo_u32_b32 v0, -1, 0
	v_mbcnt_hi_u32_b32 v0, -1, v0
	s_lshr_b32 s16, s16, 6
	s_lshl_b32 s17, s57, 3
	s_add_i32 s16, s16, s17
	v_lshlrev_b32_e32 v2, 5, v0
	v_lshlrev_b32_e32 v3, 4, v0
	v_lshlrev_b32_e32 v5, 2, v0
	v_xor_b32_e32 v6, 0x80, v5
	v_xor_b32_e32 v7, 0x40, v5
	v_xor_b32_e32 v8, 0x20, v5
	v_xor_b32_e32 v9, 0x10, v5
	v_xor_b32_e32 v10, 0x8, v5
	v_xor_b32_e32 v11, 0x4, v5
	v_mov_b32_e32 v28, 0
	v_mov_b32_e32 v29, 0
	v_mov_b32_e32 v30, 0
	v_mov_b32_e32 v31, 0
	v_mov_b32_e32 v16, 0
	v_mov_b32_e32 v17, 0
	v_mov_b32_e32 v18, 0
	v_mov_b32_e32 v19, 0
	v_mov_b32_e32 v20, 0
	v_mov_b32_e32 v21, 0
	v_mov_b32_e32 v22, 0
	v_mov_b32_e32 v23, 0
	v_mov_b32_e32 v24, 0
	s_waitcnt lgkmcnt(0)
	s_mov_b32 s17, s16
	s_mul_hi_u32 s18, s17, 0xfe03f81
	s_lshr_b32 s18, s18, 7
	s_mul_i32 s19, s18, 0x810
	s_sub_i32 s19, s17, s19
	s_lshl_b32 s20, s18, 11
	s_add_i32 s20, s20, s19
	s_add_i32 s20, s20, -16
	s_lshl_b32 s20, s20, 12
	s_lshl_b32 s21, s19, 12
	s_add_u32 s46, s8, s20
	s_addc_u32 s47, s9, 0
	s_add_u32 s20, s10, s21
	s_addc_u32 s21, s11, 0
	s_cmp_lt_u32 s19, 16
	s_cselect_b32 s46, s20, s46
	s_cselect_b32 s47, s21, s47
	global_load_dwordx4 v[32:35], v2, s[46:47] nt
	global_load_dwordx4 v[36:39], v2, s[46:47] offset:16 nt
	global_load_dwordx4 v[40:43], v2, s[46:47] offset:2048 nt
	global_load_dwordx4 v[44:47], v2, s[46:47] offset:2064 nt
	s_add_i32 s17, s16, 0x800
	s_mul_hi_u32 s18, s17, 0xfe03f81
	s_lshr_b32 s18, s18, 7
	s_mul_i32 s19, s18, 0x810
	s_sub_i32 s19, s17, s19
	s_lshl_b32 s20, s18, 11
	s_add_i32 s20, s20, s19
	s_add_i32 s20, s20, -16
	s_lshl_b32 s20, s20, 12
	s_lshl_b32 s21, s19, 12
	s_add_u32 s46, s8, s20
	s_addc_u32 s47, s9, 0
	s_add_u32 s20, s10, s21
	s_addc_u32 s21, s11, 0
	s_cmp_lt_u32 s19, 16
	s_cselect_b32 s46, s20, s46
	s_cselect_b32 s47, s21, s47
	global_load_dwordx4 v[48:51], v2, s[46:47] nt
	global_load_dwordx4 v[52:55], v2, s[46:47] offset:16 nt
	global_load_dwordx4 v[56:59], v2, s[46:47] offset:2048 nt
	global_load_dwordx4 v[60:63], v2, s[46:47] offset:2064 nt
	s_add_i32 s17, s16, 0x1000
	s_mul_hi_u32 s18, s17, 0xfe03f81
	s_lshr_b32 s18, s18, 7
	s_mul_i32 s19, s18, 0x810
	s_sub_i32 s19, s17, s19
	s_lshl_b32 s20, s18, 11
	s_add_i32 s20, s20, s19
	s_add_i32 s20, s20, -16
	s_lshl_b32 s20, s20, 12
	s_lshl_b32 s21, s19, 12
	s_add_u32 s46, s8, s20
	s_addc_u32 s47, s9, 0
	s_add_u32 s20, s10, s21
	s_addc_u32 s21, s11, 0
	s_cmp_lt_u32 s19, 16
	s_cselect_b32 s46, s20, s46
	s_cselect_b32 s47, s21, s47
	global_load_dwordx4 v[64:67], v2, s[46:47] nt
	global_load_dwordx4 v[68:71], v2, s[46:47] offset:16 nt
	global_load_dwordx4 v[72:75], v2, s[46:47] offset:2048 nt
	global_load_dwordx4 v[76:79], v2, s[46:47] offset:2064 nt
	s_add_i32 s17, s16, 0x1800
	s_mul_hi_u32 s18, s17, 0xfe03f81
	s_lshr_b32 s18, s18, 7
	s_mul_i32 s19, s18, 0x810
	s_sub_i32 s19, s17, s19
	s_lshl_b32 s20, s18, 11
	s_add_i32 s20, s20, s19
	s_add_i32 s20, s20, -16
	s_lshl_b32 s20, s20, 12
	s_lshl_b32 s21, s19, 12
	s_add_u32 s46, s8, s20
	s_addc_u32 s47, s9, 0
	s_add_u32 s20, s10, s21
	s_addc_u32 s21, s11, 0
	s_cmp_lt_u32 s19, 16
	s_cselect_b32 s46, s20, s46
	s_cselect_b32 s47, s21, s47
	global_load_dwordx4 v[80:83], v2, s[46:47] nt
	global_load_dwordx4 v[84:87], v2, s[46:47] offset:16 nt
	global_load_dwordx4 v[88:91], v2, s[46:47] offset:2048 nt
	global_load_dwordx4 v[92:95], v2, s[46:47] offset:2064 nt
	s_add_i32 s17, s16, 0x2000
	s_mul_hi_u32 s18, s17, 0xfe03f81
	s_lshr_b32 s18, s18, 7
	s_mul_i32 s19, s18, 0x810
	s_sub_i32 s19, s17, s19
	s_lshl_b32 s20, s18, 11
	s_add_i32 s20, s20, s19
	s_add_i32 s20, s20, -16
	s_lshl_b32 s20, s20, 12
	s_lshl_b32 s21, s19, 12
	s_add_u32 s46, s8, s20
	s_addc_u32 s47, s9, 0
	s_add_u32 s20, s10, s21
	s_addc_u32 s21, s11, 0
	s_cmp_lt_u32 s19, 16
	s_cselect_b32 s46, s20, s46
	s_cselect_b32 s47, s21, s47
	global_load_dwordx4 v[96:99], v2, s[46:47] nt
	global_load_dwordx4 v[100:103], v2, s[46:47] offset:16 nt
	global_load_dwordx4 v[104:107], v2, s[46:47] offset:2048 nt
	global_load_dwordx4 v[108:111], v2, s[46:47] offset:2064 nt
	s_add_i32 s17, s16, 0x2800
	s_mul_hi_u32 s18, s17, 0xfe03f81
	s_lshr_b32 s18, s18, 7
	s_mul_i32 s19, s18, 0x810
	s_sub_i32 s19, s17, s19
	s_lshl_b32 s20, s18, 11
	s_add_i32 s20, s20, s19
	s_add_i32 s20, s20, -16
	s_lshl_b32 s20, s20, 12
	s_lshl_b32 s21, s19, 12
	s_add_u32 s46, s8, s20
	s_addc_u32 s47, s9, 0
	s_add_u32 s20, s10, s21
	s_addc_u32 s21, s11, 0
	s_cmp_lt_u32 s19, 16
	s_cselect_b32 s46, s20, s46
	s_cselect_b32 s47, s21, s47
	global_load_dwordx4 v[112:115], v2, s[46:47] nt
	global_load_dwordx4 v[116:119], v2, s[46:47] offset:16 nt
	global_load_dwordx4 v[120:123], v2, s[46:47] offset:2048 nt
	global_load_dwordx4 v[124:127], v2, s[46:47] offset:2064 nt
	s_add_i32 s17, s16, 0x3000
	s_mul_hi_u32 s18, s17, 0xfe03f81
	s_lshr_b32 s18, s18, 7
	s_mul_i32 s19, s18, 0x810
	s_sub_i32 s19, s17, s19
	s_lshl_b32 s20, s18, 11
	s_add_i32 s20, s20, s19
	s_add_i32 s20, s20, -16
	s_lshl_b32 s20, s20, 12
	s_lshl_b32 s21, s19, 12
	s_add_u32 s46, s8, s20
	s_addc_u32 s47, s9, 0
	s_add_u32 s20, s10, s21
	s_addc_u32 s21, s11, 0
	s_cmp_lt_u32 s19, 16
	s_cselect_b32 s46, s20, s46
	s_cselect_b32 s47, s21, s47
	global_load_dwordx4 v[128:131], v2, s[46:47] nt
	global_load_dwordx4 v[132:135], v2, s[46:47] offset:16 nt
	global_load_dwordx4 v[136:139], v2, s[46:47] offset:2048 nt
	global_load_dwordx4 v[140:143], v2, s[46:47] offset:2064 nt
	s_add_i32 s17, s16, 0x3800
	s_mul_hi_u32 s18, s17, 0xfe03f81
	s_lshr_b32 s18, s18, 7
	s_mul_i32 s19, s18, 0x810
	s_sub_i32 s19, s17, s19
	s_lshl_b32 s20, s18, 11
	s_add_i32 s20, s20, s19
	s_add_i32 s20, s20, -16
	s_lshl_b32 s20, s20, 12
	s_lshl_b32 s21, s19, 12
	s_add_u32 s46, s8, s20
	s_addc_u32 s47, s9, 0
	s_add_u32 s20, s10, s21
	s_addc_u32 s21, s11, 0
	s_cmp_lt_u32 s19, 16
	s_cselect_b32 s46, s20, s46
	s_cselect_b32 s47, s21, s47
	global_load_dwordx4 v[144:147], v2, s[46:47] nt
	global_load_dwordx4 v[148:151], v2, s[46:47] offset:16 nt
	global_load_dwordx4 v[152:155], v2, s[46:47] offset:2048 nt
	global_load_dwordx4 v[156:159], v2, s[46:47] offset:2064 nt
	s_cmpk_lt_u32 s16, 0x80
	s_cbranch_scc0 .Lmy_xc_no8
	s_add_i32 s17, s16, 0x4000
	s_mul_hi_u32 s18, s17, 0xfe03f81
	s_lshr_b32 s18, s18, 7
	s_mul_i32 s19, s18, 0x810
	s_sub_i32 s19, s17, s19
	s_lshl_b32 s20, s18, 11
	s_add_i32 s20, s20, s19
	s_add_i32 s20, s20, -16
	s_lshl_b32 s20, s20, 12
	s_lshl_b32 s21, s19, 12
	s_add_u32 s46, s8, s20
	s_addc_u32 s47, s9, 0
	s_add_u32 s20, s10, s21
	s_addc_u32 s21, s11, 0
	s_cmp_lt_u32 s19, 16
	s_cselect_b32 s46, s20, s46
	s_cselect_b32 s47, s21, s47
	global_load_dwordx4 v[160:163], v2, s[46:47] nt
	global_load_dwordx4 v[164:167], v2, s[46:47] offset:16 nt
	global_load_dwordx4 v[168:171], v2, s[46:47] offset:2048 nt
	global_load_dwordx4 v[172:175], v2, s[46:47] offset:2064 nt
.Lmy_xc_no8:
	s_waitcnt vmcnt(28)
	v_mul_f32_e32 v16, v32, v32
	v_fmac_f32_e32 v16, v33, v33
	v_fmac_f32_e32 v16, v34, v34
	v_fmac_f32_e32 v16, v35, v35
	v_fmac_f32_e32 v16, v36, v36
	v_fmac_f32_e32 v16, v37, v37
	v_fmac_f32_e32 v16, v38, v38
	v_fmac_f32_e32 v16, v39, v39
	v_fmac_f32_e32 v16, v40, v40
	v_fmac_f32_e32 v16, v41, v41
	v_fmac_f32_e32 v16, v42, v42
	v_fmac_f32_e32 v16, v43, v43
	v_fmac_f32_e32 v16, v44, v44
	v_fmac_f32_e32 v16, v45, v45
	v_fmac_f32_e32 v16, v46, v46
	v_fmac_f32_e32 v16, v47, v47
	v_cvt_pk_bf16_f32 v32, v32, v33
	v_cvt_pk_bf16_f32 v33, v34, v35
	v_cvt_pk_bf16_f32 v34, v36, v37
	v_cvt_pk_bf16_f32 v35, v38, v39
	v_cvt_pk_bf16_f32 v36, v40, v41
	v_cvt_pk_bf16_f32 v37, v42, v43
	v_cvt_pk_bf16_f32 v38, v44, v45
	v_cvt_pk_bf16_f32 v39, v46, v47
	s_lshl_b32 s17, s16, 11
	v_add_u32_e32 v4, s17, v3
	global_store_dwordx4 v4, v[32:35], s[12:13]
	global_store_dwordx4 v4, v[36:39], s[12:13] offset:1024
	s_waitcnt vmcnt(26)
	v_mul_f32_e32 v17, v48, v48
	v_fmac_f32_e32 v17, v49, v49
	v_fmac_f32_e32 v17, v50, v50
	v_fmac_f32_e32 v17, v51, v51
	v_fmac_f32_e32 v17, v52, v52
	v_fmac_f32_e32 v17, v53, v53
	v_fmac_f32_e32 v17, v54, v54
	v_fmac_f32_e32 v17, v55, v55
	v_fmac_f32_e32 v17, v56, v56
	v_fmac_f32_e32 v17, v57, v57
	v_fmac_f32_e32 v17, v58, v58
	v_fmac_f32_e32 v17, v59, v59
	v_fmac_f32_e32 v17, v60, v60
	v_fmac_f32_e32 v17, v61, v61
	v_fmac_f32_e32 v17, v62, v62
	v_fmac_f32_e32 v17, v63, v63
	v_cvt_pk_bf16_f32 v48, v48, v49
	v_cvt_pk_bf16_f32 v49, v50, v51
	v_cvt_pk_bf16_f32 v50, v52, v53
	v_cvt_pk_bf16_f32 v51, v54, v55
	v_cvt_pk_bf16_f32 v52, v56, v57
	v_cvt_pk_bf16_f32 v53, v58, v59
	v_cvt_pk_bf16_f32 v54, v60, v61
	v_cvt_pk_bf16_f32 v55, v62, v63
	s_add_i32 s17, s16, 0x800
	s_lshl_b32 s17, s17, 11
	v_add_u32_e32 v4, s17, v3
	global_store_dwordx4 v4, v[48:51], s[12:13]
	global_store_dwordx4 v4, v[52:55], s[12:13] offset:1024
	s_waitcnt vmcnt(24)
	v_mul_f32_e32 v18, v64, v64
	v_fmac_f32_e32 v18, v65, v65
	v_fmac_f32_e32 v18, v66, v66
	v_fmac_f32_e32 v18, v67, v67
	v_fmac_f32_e32 v18, v68, v68
	v_fmac_f32_e32 v18, v69, v69
	v_fmac_f32_e32 v18, v70, v70
	v_fmac_f32_e32 v18, v71, v71
	v_fmac_f32_e32 v18, v72, v72
	v_fmac_f32_e32 v18, v73, v73
	v_fmac_f32_e32 v18, v74, v74
	v_fmac_f32_e32 v18, v75, v75
	v_fmac_f32_e32 v18, v76, v76
	v_fmac_f32_e32 v18, v77, v77
	v_fmac_f32_e32 v18, v78, v78
	v_fmac_f32_e32 v18, v79, v79
	v_cvt_pk_bf16_f32 v64, v64, v65
	v_cvt_pk_bf16_f32 v65, v66, v67
	v_cvt_pk_bf16_f32 v66, v68, v69
	v_cvt_pk_bf16_f32 v67, v70, v71
	v_cvt_pk_bf16_f32 v68, v72, v73
	v_cvt_pk_bf16_f32 v69, v74, v75
	v_cvt_pk_bf16_f32 v70, v76, v77
	v_cvt_pk_bf16_f32 v71, v78, v79
	s_add_i32 s17, s16, 0x1000
	s_lshl_b32 s17, s17, 11
	v_add_u32_e32 v4, s17, v3
	global_store_dwordx4 v4, v[64:67], s[12:13]
	global_store_dwordx4 v4, v[68:71], s[12:13] offset:1024
	s_waitcnt vmcnt(22)
	v_mul_f32_e32 v19, v80, v80
	v_fmac_f32_e32 v19, v81, v81
	v_fmac_f32_e32 v19, v82, v82
	v_fmac_f32_e32 v19, v83, v83
	v_fmac_f32_e32 v19, v84, v84
	v_fmac_f32_e32 v19, v85, v85
	v_fmac_f32_e32 v19, v86, v86
	v_fmac_f32_e32 v19, v87, v87
	v_fmac_f32_e32 v19, v88, v88
	v_fmac_f32_e32 v19, v89, v89
	v_fmac_f32_e32 v19, v90, v90
	v_fmac_f32_e32 v19, v91, v91
	v_fmac_f32_e32 v19, v92, v92
	v_fmac_f32_e32 v19, v93, v93
	v_fmac_f32_e32 v19, v94, v94
	v_fmac_f32_e32 v19, v95, v95
	v_cvt_pk_bf16_f32 v80, v80, v81
	v_cvt_pk_bf16_f32 v81, v82, v83
	v_cvt_pk_bf16_f32 v82, v84, v85
	v_cvt_pk_bf16_f32 v83, v86, v87
	v_cvt_pk_bf16_f32 v84, v88, v89
	v_cvt_pk_bf16_f32 v85, v90, v91
	v_cvt_pk_bf16_f32 v86, v92, v93
	v_cvt_pk_bf16_f32 v87, v94, v95
	s_add_i32 s17, s16, 0x1800
	s_lshl_b32 s17, s17, 11
	v_add_u32_e32 v4, s17, v3
	global_store_dwordx4 v4, v[80:83], s[12:13]
	global_store_dwordx4 v4, v[84:87], s[12:13] offset:1024
	s_waitcnt vmcnt(20)
	v_mul_f32_e32 v20, v96, v96
	v_fmac_f32_e32 v20, v97, v97
	v_fmac_f32_e32 v20, v98, v98
	v_fmac_f32_e32 v20, v99, v99
	v_fmac_f32_e32 v20, v100, v100
	v_fmac_f32_e32 v20, v101, v101
	v_fmac_f32_e32 v20, v102, v102
	v_fmac_f32_e32 v20, v103, v103
	v_fmac_f32_e32 v20, v104, v104
	v_fmac_f32_e32 v20, v105, v105
	v_fmac_f32_e32 v20, v106, v106
	v_fmac_f32_e32 v20, v107, v107
	v_fmac_f32_e32 v20, v108, v108
	v_fmac_f32_e32 v20, v109, v109
	v_fmac_f32_e32 v20, v110, v110
	v_fmac_f32_e32 v20, v111, v111
	v_cvt_pk_bf16_f32 v96, v96, v97
	v_cvt_pk_bf16_f32 v97, v98, v99
	v_cvt_pk_bf16_f32 v98, v100, v101
	v_cvt_pk_bf16_f32 v99, v102, v103
	v_cvt_pk_bf16_f32 v100, v104, v105
	v_cvt_pk_bf16_f32 v101, v106, v107
	v_cvt_pk_bf16_f32 v102, v108, v109
	v_cvt_pk_bf16_f32 v103, v110, v111
	s_add_i32 s17, s16, 0x2000
	s_lshl_b32 s17, s17, 11
	v_add_u32_e32 v4, s17, v3
	global_store_dwordx4 v4, v[96:99], s[12:13]
	global_store_dwordx4 v4, v[100:103], s[12:13] offset:1024
	s_waitcnt vmcnt(18)
	v_mul_f32_e32 v21, v112, v112
	v_fmac_f32_e32 v21, v113, v113
	v_fmac_f32_e32 v21, v114, v114
	v_fmac_f32_e32 v21, v115, v115
	v_fmac_f32_e32 v21, v116, v116
	v_fmac_f32_e32 v21, v117, v117
	v_fmac_f32_e32 v21, v118, v118
	v_fmac_f32_e32 v21, v119, v119
	v_fmac_f32_e32 v21, v120, v120
	v_fmac_f32_e32 v21, v121, v121
	v_fmac_f32_e32 v21, v122, v122
	v_fmac_f32_e32 v21, v123, v123
	v_fmac_f32_e32 v21, v124, v124
	v_fmac_f32_e32 v21, v125, v125
	v_fmac_f32_e32 v21, v126, v126
	v_fmac_f32_e32 v21, v127, v127
	v_cvt_pk_bf16_f32 v112, v112, v113
	v_cvt_pk_bf16_f32 v113, v114, v115
	v_cvt_pk_bf16_f32 v114, v116, v117
	v_cvt_pk_bf16_f32 v115, v118, v119
	v_cvt_pk_bf16_f32 v116, v120, v121
	v_cvt_pk_bf16_f32 v117, v122, v123
	v_cvt_pk_bf16_f32 v118, v124, v125
	v_cvt_pk_bf16_f32 v119, v126, v127
	s_add_i32 s17, s16, 0x2800
	s_lshl_b32 s17, s17, 11
	v_add_u32_e32 v4, s17, v3
	global_store_dwordx4 v4, v[112:115], s[12:13]
	global_store_dwordx4 v4, v[116:119], s[12:13] offset:1024
	s_waitcnt vmcnt(16)
	v_mul_f32_e32 v22, v128, v128
	v_fmac_f32_e32 v22, v129, v129
	v_fmac_f32_e32 v22, v130, v130
	v_fmac_f32_e32 v22, v131, v131
	v_fmac_f32_e32 v22, v132, v132
	v_fmac_f32_e32 v22, v133, v133
	v_fmac_f32_e32 v22, v134, v134
	v_fmac_f32_e32 v22, v135, v135
	v_fmac_f32_e32 v22, v136, v136
	v_fmac_f32_e32 v22, v137, v137
	v_fmac_f32_e32 v22, v138, v138
	v_fmac_f32_e32 v22, v139, v139
	v_fmac_f32_e32 v22, v140, v140
	v_fmac_f32_e32 v22, v141, v141
	v_fmac_f32_e32 v22, v142, v142
	v_fmac_f32_e32 v22, v143, v143
	v_cvt_pk_bf16_f32 v128, v128, v129
	v_cvt_pk_bf16_f32 v129, v130, v131
	v_cvt_pk_bf16_f32 v130, v132, v133
	v_cvt_pk_bf16_f32 v131, v134, v135
	v_cvt_pk_bf16_f32 v132, v136, v137
	v_cvt_pk_bf16_f32 v133, v138, v139
	v_cvt_pk_bf16_f32 v134, v140, v141
	v_cvt_pk_bf16_f32 v135, v142, v143
	s_add_i32 s17, s16, 0x3000
	s_lshl_b32 s17, s17, 11
	v_add_u32_e32 v4, s17, v3
	global_store_dwordx4 v4, v[128:131], s[12:13]
	global_store_dwordx4 v4, v[132:135], s[12:13] offset:1024
	s_waitcnt vmcnt(14)
	v_mul_f32_e32 v23, v144, v144
	v_fmac_f32_e32 v23, v145, v145
	v_fmac_f32_e32 v23, v146, v146
	v_fmac_f32_e32 v23, v147, v147
	v_fmac_f32_e32 v23, v148, v148
	v_fmac_f32_e32 v23, v149, v149
	v_fmac_f32_e32 v23, v150, v150
	v_fmac_f32_e32 v23, v151, v151
	v_fmac_f32_e32 v23, v152, v152
	v_fmac_f32_e32 v23, v153, v153
	v_fmac_f32_e32 v23, v154, v154
	v_fmac_f32_e32 v23, v155, v155
	v_fmac_f32_e32 v23, v156, v156
	v_fmac_f32_e32 v23, v157, v157
	v_fmac_f32_e32 v23, v158, v158
	v_fmac_f32_e32 v23, v159, v159
	v_cvt_pk_bf16_f32 v144, v144, v145
	v_cvt_pk_bf16_f32 v145, v146, v147
	v_cvt_pk_bf16_f32 v146, v148, v149
	v_cvt_pk_bf16_f32 v147, v150, v151
	v_cvt_pk_bf16_f32 v148, v152, v153
	v_cvt_pk_bf16_f32 v149, v154, v155
	v_cvt_pk_bf16_f32 v150, v156, v157
	v_cvt_pk_bf16_f32 v151, v158, v159
	s_add_i32 s17, s16, 0x3800
	s_lshl_b32 s17, s17, 11
	v_add_u32_e32 v4, s17, v3
	global_store_dwordx4 v4, v[144:147], s[12:13]
	global_store_dwordx4 v4, v[148:151], s[12:13] offset:1024
	s_cmpk_lt_u32 s16, 0x80
	s_cbranch_scc0 .Lmy_xc_pad
	s_waitcnt vmcnt(16)
	v_mul_f32_e32 v24, v160, v160
	v_fmac_f32_e32 v24, v161, v161
	v_fmac_f32_e32 v24, v162, v162
	v_fmac_f32_e32 v24, v163, v163
	v_fmac_f32_e32 v24, v164, v164
	v_fmac_f32_e32 v24, v165, v165
	v_fmac_f32_e32 v24, v166, v166
	v_fmac_f32_e32 v24, v167, v167
	v_fmac_f32_e32 v24, v168, v168
	v_fmac_f32_e32 v24, v169, v169
	v_fmac_f32_e32 v24, v170, v170
	v_fmac_f32_e32 v24, v171, v171
	v_fmac_f32_e32 v24, v172, v172
	v_fmac_f32_e32 v24, v173, v173
	v_fmac_f32_e32 v24, v174, v174
	v_fmac_f32_e32 v24, v175, v175
	v_cvt_pk_bf16_f32 v160, v160, v161
	v_cvt_pk_bf16_f32 v161, v162, v163
	v_cvt_pk_bf16_f32 v162, v164, v165
	v_cvt_pk_bf16_f32 v163, v166, v167
	v_cvt_pk_bf16_f32 v164, v168, v169
	v_cvt_pk_bf16_f32 v165, v170, v171
	v_cvt_pk_bf16_f32 v166, v172, v173
	v_cvt_pk_bf16_f32 v167, v174, v175
	s_add_i32 s17, s16, 0x4000
	s_lshl_b32 s17, s17, 11
	v_add_u32_e32 v4, s17, v3
	global_store_dwordx4 v4, v[160:163], s[12:13]
	global_store_dwordx4 v4, v[164:167], s[12:13] offset:1024
	s_branch .Lmy_xc_red
.Lmy_xc_pad:
	s_cmpk_lt_u32 s16, 0x100
	s_cbranch_scc0 .Lmy_xc_red
	s_add_i32 s17, s16, 0x4000
	s_lshl_b32 s17, s17, 11
	v_add_u32_e32 v4, s17, v3
	global_store_dwordx4 v4, v[28:31], s[12:13]
	global_store_dwordx4 v4, v[28:31], s[12:13] offset:1024
.Lmy_xc_red:
	ds_bpermute_b32 v32, v6, v16
	ds_bpermute_b32 v33, v6, v17
	ds_bpermute_b32 v34, v6, v18
	ds_bpermute_b32 v35, v6, v19
	ds_bpermute_b32 v36, v6, v20
	ds_bpermute_b32 v37, v6, v21
	ds_bpermute_b32 v38, v6, v22
	ds_bpermute_b32 v39, v6, v23
	ds_bpermute_b32 v40, v6, v24
	s_waitcnt lgkmcnt(0)
	v_add_f32_e32 v16, v16, v32
	v_add_f32_e32 v17, v17, v33
	v_add_f32_e32 v18, v18, v34
	v_add_f32_e32 v19, v19, v35
	v_add_f32_e32 v20, v20, v36
	v_add_f32_e32 v21, v21, v37
	v_add_f32_e32 v22, v22, v38
	v_add_f32_e32 v23, v23, v39
	v_add_f32_e32 v24, v24, v40
	ds_bpermute_b32 v32, v7, v16
	ds_bpermute_b32 v33, v7, v17
	ds_bpermute_b32 v34, v7, v18
	ds_bpermute_b32 v35, v7, v19
	ds_bpermute_b32 v36, v7, v20
	ds_bpermute_b32 v37, v7, v21
	ds_bpermute_b32 v38, v7, v22
	ds_bpermute_b32 v39, v7, v23
	ds_bpermute_b32 v40, v7, v24
	s_waitcnt lgkmcnt(0)
	v_add_f32_e32 v16, v16, v32
	v_add_f32_e32 v17, v17, v33
	v_add_f32_e32 v18, v18, v34
	v_add_f32_e32 v19, v19, v35
	v_add_f32_e32 v20, v20, v36
	v_add_f32_e32 v21, v21, v37
	v_add_f32_e32 v22, v22, v38
	v_add_f32_e32 v23, v23, v39
	v_add_f32_e32 v24, v24, v40
	ds_bpermute_b32 v32, v8, v16
	ds_bpermute_b32 v33, v8, v17
	ds_bpermute_b32 v34, v8, v18
	ds_bpermute_b32 v35, v8, v19
	ds_bpermute_b32 v36, v8, v20
	ds_bpermute_b32 v37, v8, v21
	ds_bpermute_b32 v38, v8, v22
	ds_bpermute_b32 v39, v8, v23
	ds_bpermute_b32 v40, v8, v24
	s_waitcnt lgkmcnt(0)
	v_add_f32_e32 v16, v16, v32
	v_add_f32_e32 v17, v17, v33
	v_add_f32_e32 v18, v18, v34
	v_add_f32_e32 v19, v19, v35
	v_add_f32_e32 v20, v20, v36
	v_add_f32_e32 v21, v21, v37
	v_add_f32_e32 v22, v22, v38
	v_add_f32_e32 v23, v23, v39
	v_add_f32_e32 v24, v24, v40
	ds_bpermute_b32 v32, v9, v16
	ds_bpermute_b32 v33, v9, v17
	ds_bpermute_b32 v34, v9, v18
	ds_bpermute_b32 v35, v9, v19
	ds_bpermute_b32 v36, v9, v20
	ds_bpermute_b32 v37, v9, v21
	ds_bpermute_b32 v38, v9, v22
	ds_bpermute_b32 v39, v9, v23
	ds_bpermute_b32 v40, v9, v24
	s_waitcnt lgkmcnt(0)
	v_add_f32_e32 v16, v16, v32
	v_add_f32_e32 v17, v17, v33
	v_add_f32_e32 v18, v18, v34
	v_add_f32_e32 v19, v19, v35
	v_add_f32_e32 v20, v20, v36
	v_add_f32_e32 v21, v21, v37
	v_add_f32_e32 v22, v22, v38
	v_add_f32_e32 v23, v23, v39
	v_add_f32_e32 v24, v24, v40
	ds_bpermute_b32 v32, v10, v16
	ds_bpermute_b32 v33, v10, v17
	ds_bpermute_b32 v34, v10, v18
	ds_bpermute_b32 v35, v10, v19
	ds_bpermute_b32 v36, v10, v20
	ds_bpermute_b32 v37, v10, v21
	ds_bpermute_b32 v38, v10, v22
	ds_bpermute_b32 v39, v10, v23
	ds_bpermute_b32 v40, v10, v24
	s_waitcnt lgkmcnt(0)
	v_add_f32_e32 v16, v16, v32
	v_add_f32_e32 v17, v17, v33
	v_add_f32_e32 v18, v18, v34
	v_add_f32_e32 v19, v19, v35
	v_add_f32_e32 v20, v20, v36
	v_add_f32_e32 v21, v21, v37
	v_add_f32_e32 v22, v22, v38
	v_add_f32_e32 v23, v23, v39
	v_add_f32_e32 v24, v24, v40
	ds_bpermute_b32 v32, v11, v16
	ds_bpermute_b32 v33, v11, v17
	ds_bpermute_b32 v34, v11, v18
	ds_bpermute_b32 v35, v11, v19
	ds_bpermute_b32 v36, v11, v20
	ds_bpermute_b32 v37, v11, v21
	ds_bpermute_b32 v38, v11, v22
	ds_bpermute_b32 v39, v11, v23
	ds_bpermute_b32 v40, v11, v24
	s_waitcnt lgkmcnt(0)
	v_add_f32_e32 v16, v16, v32
	v_add_f32_e32 v17, v17, v33
	v_add_f32_e32 v18, v18, v34
	v_add_f32_e32 v19, v19, v35
	v_add_f32_e32 v20, v20, v36
	v_add_f32_e32 v21, v21, v37
	v_add_f32_e32 v22, v22, v38
	v_add_f32_e32 v23, v23, v39
	v_add_f32_e32 v24, v24, v40
	s_mov_b64 exec, 1
	s_lshl_b32 s17, s16, 2
	v_mov_b32_e32 v4, s17
	global_store_dword v4, v16, s[14:15]
	s_add_i32 s17, s16, 0x800
	s_lshl_b32 s17, s17, 2
	v_mov_b32_e32 v4, s17
	global_store_dword v4, v17, s[14:15]
	s_add_i32 s17, s16, 0x1000
	s_lshl_b32 s17, s17, 2
	v_mov_b32_e32 v4, s17
	global_store_dword v4, v18, s[14:15]
	s_add_i32 s17, s16, 0x1800
	s_lshl_b32 s17, s17, 2
	v_mov_b32_e32 v4, s17
	global_store_dword v4, v19, s[14:15]
	s_add_i32 s17, s16, 0x2000
	s_lshl_b32 s17, s17, 2
	v_mov_b32_e32 v4, s17
	global_store_dword v4, v20, s[14:15]
	s_add_i32 s17, s16, 0x2800
	s_lshl_b32 s17, s17, 2
	v_mov_b32_e32 v4, s17
	global_store_dword v4, v21, s[14:15]
	s_add_i32 s17, s16, 0x3000
	s_lshl_b32 s17, s17, 2
	v_mov_b32_e32 v4, s17
	global_store_dword v4, v22, s[14:15]
	s_add_i32 s17, s16, 0x3800
	s_lshl_b32 s17, s17, 2
	v_mov_b32_e32 v4, s17
	global_store_dword v4, v23, s[14:15]
	s_cmpk_lt_u32 s16, 0x100
	s_cbranch_scc0 .Lmy_xc_done
	s_add_i32 s17, s16, 0x4000
	s_lshl_b32 s17, s17, 2
	v_mov_b32_e32 v4, s17
	global_store_dword v4, v24, s[14:15]
.Lmy_xc_done:
	s_mov_b64 exec, -1
	s_branch .Lmy_xc_exit
.Lmy_xc_exit:
	s_getpc_b64 s[98:99]
.Lpost_getpc7:
	s_add_u32 s98, s98, (.LBB0_10-.Lpost_getpc7)&4294967295
	s_addc_u32 s99, s99, (.LBB0_10-.Lpost_getpc7)>>32
	s_setpc_b64 s[98:99]
.LBB0_1494:
	v_readlane_b32 s88, v255, 33
	v_readlane_b32 s89, v255, 34
	s_add_i32 s88, s88, 1
	s_cmp_lt_i32 s88, s89
	s_mov_b64 s[2:3], -1
	v_readlane_b32 s90, v252, 19
	s_cbranch_scc1 .LBB0_1495
	s_getpc_b64 s[98:99]
